# mix0 SGU loop: next item's v tile fetched during the current item's MFMA chain and epilogue into spare registers, epilogue waits only for its own u values
# baseline (speedup 1.0000x reference)
; #define LAS __attribute__((address_space(3)))
; __device__ __forceinline__ void phase_mix0(const Params& p, LAS unsigned char* lds) {
;     ...
;     const float* ST = (const float*)(p.ws + WS_STATS); const h16* WSH = (const h16*)(p.ws + WS_WSH);
;     const float* lng = p.in[4]; const float* lnb = p.in[5]; const float* bs = p.in[7];
;     LAS h16* vnT = (LAS h16*)lds;
;     for (int it = blockIdx.x; it < 1024; it += gridDim.x) {
;         const int g = it & 7, bn = it >> 3, t0 = bn * 128;
;         __syncthreads();
; #pragma unroll
;         for (int q = 0; q < 4; ++q) { const int pc = tid + 512 * q, j = pc >> 4, d8 = (pc & 15) * 8;
;             const h16x8 v = *(const h16x8*)(V + (size_t)(t0 + j) * 1024 + g * 128 + d8);
;             const float mu = ST[2 * (t0 + j)] * (1.f / 1024.f), rs = rsqrtf(fmaxf(ST[2 * (t0 + j) + 1] * (1.f / 1024.f) - mu * mu, 0.f) + 1e-5f);
; #pragma unroll
;             for (int e = 0; e < 8; ++e) vnT[(d8 + e) * 136 + ((((j >> 3) ^ (pc & 15)) << 3) | (j & 7))] = (h16)(((float)v[e] - mu) * rs * lng[g * 128 + d8 + e] + lnb[g * 128 + d8 + e]); }
;         __syncthreads();
;         const int itile = wave >> 1, dt0 = (wave & 1) * 2;
;         f32x16 acc0, acc1;
; #pragma unroll
;         for (int e = 0; e < 16; ++e) { acc0[e] = 0.f; acc1[e] = 0.f; }
;         const h16* Arow = WSH + ((size_t)g * 128 + itile * 32 + (lane & 31)) * 128 + 8 * (lane >> 5);
;         const int d0_ = dt0 * 32 + (lane & 31), d1_ = d0_ + 32;
;         const LAS h16* B0p = vnT + d0_ * 136; const LAS h16* B1p = vnT + d1_ * 136;
.LBB0_287:
	s_or_b64 exec, exec, s[0:1]
	s_cmpk_gt_i32 s2, 0x3ff
	s_cbranch_scc1 .LBB0_290
	v_and_b32_e32 v2, 15, v130
	v_lshlrev_b32_e32 v32, 4, v2
	v_mov_b32_e32 v33, 0
	v_lshl_add_u64 v[0:1], s[70:71], 0, v[32:33]
	s_mov_b64 s[0:1], 0x8400000
	v_bfe_u32 v4, v130, 5, 1
	v_lshl_add_u64 v[34:35], v[0:1], 0, s[0:1]
	v_lshrrev_b32_e32 v0, 2, v130
	v_lshlrev_b32_e32 v32, 4, v4
	v_and_b32_e32 v3, 0xe0, v0
	v_lshl_add_u64 v[0:1], s[70:71], 0, v[32:33]
	s_mov_b64 s[0:1], 0x2020000
	v_lshl_add_u64 v[36:37], v[0:1], 0, s[0:1]
	v_and_b32_e32 v44, 0x5f, v130
	s_movk_i32 s0, 0x110
	v_lshlrev_b32_e32 v5, 3, v4
	v_or_b32_e32 v0, 32, v44
	v_mad_u32_u24 v1, v44, s0, 0
	s_movk_i32 s1, 0x78
	v_add_u32_e32 v6, 0x2200, v1
	v_and_b32_e32 v7, 0x58, v130
	v_bitop3_b32 v0, v5, v0, s1 bitop3:0x78
	v_bitop3_b32 v8, v44, s1, 32 bitop3:0xc8
	v_lshl_add_u32 v51, v0, 1, v6
	v_bitop3_b32 v0, v5, v7, 16 bitop3:0x36
	v_lshl_add_u32 v52, v0, 1, v1
	v_bitop3_b32 v0, v5, v8, 16 bitop3:0x36
	v_lshl_add_u32 v53, v0, 1, v6
	v_bitop3_b32 v0, v5, v7, 32 bitop3:0x36
	v_add_u32_e32 v9, 0x200, v130
	v_or_b32_e32 v10, 0x400, v130
	v_add_u32_e32 v11, 0x600, v130
	v_lshl_add_u32 v54, v0, 1, v1
	v_bitop3_b32 v0, v5, v8, 32 bitop3:0x36
	v_and_or_b32 v43, v130, 31, v3
	v_lshl_or_b32 v45, v4, 2, v3
	v_lshrrev_b32_e32 v3, 7, v130
	v_lshrrev_b32_e32 v47, 4, v9
	v_lshrrev_b32_e32 v9, 7, v9
	v_lshrrev_b32_e32 v48, 4, v10
	v_lshrrev_b32_e32 v10, 7, v10
	v_lshrrev_b32_e32 v49, 4, v11
	v_lshrrev_b32_e32 v11, 7, v11
	v_lshl_add_u32 v55, v0, 1, v6
	v_bitop3_b32 v0, v5, v7, 48 bitop3:0x36
	v_bitop3_b32 v3, v3, v130, 15 bitop3:0x78
	v_lshrrev_b32_e32 v4, 3, v130
	v_bitop3_b32 v9, v9, v130, 15 bitop3:0x78
	v_bitop3_b32 v10, v10, v130, 15 bitop3:0x78
	v_bitop3_b32 v11, v11, v130, 15 bitop3:0x78
	v_lshl_add_u32 v56, v0, 1, v1
	v_bitop3_b32 v0, v5, v8, 48 bitop3:0x36
	s_movk_i32 s0, 0x58
	v_lshlrev_b32_e32 v3, 4, v3
	v_and_b32_e32 v4, 14, v4
	v_lshlrev_b32_e32 v9, 4, v9
	v_lshlrev_b32_e32 v10, 4, v10
	v_lshlrev_b32_e32 v11, 4, v11
	v_lshl_add_u32 v57, v0, 1, v6
	v_bitop3_b32 v0, v5, v7, 64 bitop3:0x36
	v_add3_u32 v3, 0, v3, v4
	v_add3_u32 v9, 0, v9, v4
	v_add3_u32 v10, 0, v10, v4
	v_add3_u32 v4, 0, v11, v4
	v_bitop3_b32 v11, v5, v130, s0 bitop3:0x78
	v_lshl_add_u32 v58, v0, 1, v1
	v_bitop3_b32 v0, v5, v8, 64 bitop3:0x36
	s_movk_i32 s0, 0x50
	v_lshl_add_u32 v59, v0, 1, v6
	v_bitop3_b32 v0, v5, v7, s0 bitop3:0x36
	v_lshl_add_u32 v60, v0, 1, v1
	v_bitop3_b32 v0, v5, v8, s0 bitop3:0x36
	s_movk_i32 s0, 0x60
	v_lshl_add_u32 v61, v0, 1, v6
	v_bitop3_b32 v0, v5, v7, s0 bitop3:0x36
	s_add_u32 s12, s70, 0x6400000
	v_lshl_add_u32 v62, v0, 1, v1
	v_bitop3_b32 v0, v5, v8, s0 bitop3:0x36
	s_movk_i32 s0, 0x70
	s_addc_u32 s13, s71, 0
	v_lshl_add_u32 v63, v0, 1, v6
	v_bitop3_b32 v0, v5, v7, s0 bitop3:0x36
	s_waitcnt lgkmcnt(0)
	s_add_u32 s18, s70, 0x2000000
	v_lshlrev_b32_e32 v42, 3, v2
	v_mul_u32_u24_e32 v2, 0x880, v2
	v_lshl_add_u32 v64, v0, 1, v1
	v_bitop3_b32 v0, v5, v8, s0 bitop3:0x36
	s_addc_u32 s19, s71, 0
	s_mov_b32 s21, 0
	v_lshrrev_b32_e32 v46, 4, v130
	v_lshl_add_u32 v50, v11, 1, v1
	v_lshl_add_u32 v65, v0, 1, v6
	v_or_b32_e32 v66, 1, v45
	v_or_b32_e32 v67, 2, v45
	v_or_b32_e32 v68, 3, v45
	v_or_b32_e32 v69, 8, v45
	v_or_b32_e32 v70, 9, v45
	v_or_b32_e32 v71, 10, v45
	v_or_b32_e32 v72, 11, v45
	v_or_b32_e32 v73, 16, v45
	v_or_b32_e32 v74, 17, v45
	v_or_b32_e32 v75, 18, v45
	v_or_b32_e32 v76, 19, v45
	v_or_b32_e32 v77, 24, v45
	v_or_b32_e32 v78, 25, v45
	v_or_b32_e32 v79, 26, v45
	v_or_b32_e32 v80, 27, v45
	s_lshl_b32 s23, s2, 7
	s_lshl_b32 s28, s74, 7
	s_lshl_b32 s29, s2, 4
	s_lshl_b32 s33, s74, 4
	s_mov_b32 s22, 0x3a800000
	s_mov_b32 s46, 0x800000
	v_add_u32_e32 v81, v3, v2
	v_add_u32_e32 v82, v9, v2
	v_add_u32_e32 v83, v10, v2
	v_add_u32_e32 v84, v4, v2
	s_mov_b32 s47, s2
	s_and_b32 s48, s29, 0xffffff80
	s_and_b32 s14, s23, 0x380
	v_or_b32_e32 v0, s48, v46
	v_or_b32_e32 v16, s48, v47
	v_or_b32_e32 v18, s48, v48
	v_add_u32_e32 v20, s48, v49
	s_lshl_b32 s20, s14, 1
	v_ashrrev_i32_e32 v1, 31, v0
	v_lshlrev_b32_e32 v24, 1, v0
	v_ashrrev_i32_e32 v17, 31, v16
	v_lshlrev_b32_e32 v26, 1, v16
	v_ashrrev_i32_e32 v19, 31, v18
	v_lshlrev_b32_e32 v28, 1, v18
	v_lshlrev_b32_e32 v30, 1, v20
	v_or_b32_e32 v2, s14, v42
	v_lshl_add_u64 v[22:23], v[34:35], 0, s[20:21]
	v_ashrrev_i32_e32 v21, 31, v20
	v_lshlrev_b64 v[40:41], 11, v[0:1]
	v_ashrrev_i32_e32 v25, 31, v24
	v_lshlrev_b64 v[16:17], 11, v[16:17]
	v_ashrrev_i32_e32 v27, 31, v26
	v_lshlrev_b64 v[18:19], 11, v[18:19]
	v_ashrrev_i32_e32 v29, 31, v28
	v_ashrrev_i32_e32 v31, 31, v30
	v_lshlrev_b32_e32 v12, 2, v2
	v_lshlrev_b64 v[20:21], 11, v[20:21]
	v_lshl_add_u64 v[40:41], v[22:23], 0, v[40:41]
	v_lshl_add_u64 v[24:25], v[24:25], 2, s[18:19]
	v_lshl_add_u64 v[86:87], v[22:23], 0, v[16:17]
	v_lshl_add_u64 v[26:27], v[26:27], 2, s[18:19]
	v_lshl_add_u64 v[88:89], v[22:23], 0, v[18:19]
	v_lshl_add_u64 v[28:29], v[28:29], 2, s[18:19]
	v_lshl_add_u64 v[30:31], v[30:31], 2, s[18:19]
	v_lshl_add_u64 v[90:91], v[22:23], 0, v[20:21]
	global_load_dwordx4 v[226:229], v[40:41], off
	global_load_dwordx4 v[230:233], v[86:87], off
	global_load_dwordx4 v[234:237], v[88:89], off
	global_load_dwordx4 v[238:241], v[90:91], off
; __device__ __forceinline__ void phase_mix0(const Params& p, LAS unsigned char* lds) {
;     ...
;     for (int it = blockIdx.x; it < 1024; it += gridDim.x) {
;         const int g = it & 7, bn = it >> 3, t0 = bn * 128;
;         __syncthreads();
; #pragma unroll
;         for (int q = 0; q < 4; ++q) { const int pc = tid + 512 * q, j = pc >> 4, d8 = (pc & 15) * 8;
;             const h16x8 v = *(const h16x8*)(V + (size_t)(t0 + j) * 1024 + g * 128 + d8);
;     ...
;         for (int r = 0; r < 16; ++r) { const int i = itile * 32 + (r & 3) + 8 * (r >> 2) + 4 * (lane >> 5); const size_t t = (size_t)(t0 + i);
;             const float bias = bs[g * 128 + i];
;             const int d0 = g * 128 + dt0 * 32 + (lane & 31);
;             YC[t * 2048 + 1024 + d0] = (h16)((acc0[r] + bias) * (float)U[t * 1024 + d0]);
;             YC[t * 2048 + 1024 + d0 + 32] = (h16)((acc1[r] + bias) * (float)U[t * 1024 + d0 + 32]); }
.LBB0_289:
	s_and_b32 s48, s29, 0xffffff80
	s_and_b32 s14, s23, 0x380
	v_or_b32_e32 v0, s48, v46
	v_or_b32_e32 v16, s48, v47
	v_or_b32_e32 v18, s48, v48
	v_add_u32_e32 v20, s48, v49
	s_lshl_b32 s20, s14, 1
	v_ashrrev_i32_e32 v1, 31, v0
	v_lshlrev_b32_e32 v24, 1, v0
	v_ashrrev_i32_e32 v17, 31, v16
	v_lshlrev_b32_e32 v26, 1, v16
	v_ashrrev_i32_e32 v19, 31, v18
	v_lshlrev_b32_e32 v28, 1, v18
	v_lshlrev_b32_e32 v30, 1, v20
	v_or_b32_e32 v2, s14, v42
	v_lshl_add_u64 v[22:23], v[34:35], 0, s[20:21]
	v_ashrrev_i32_e32 v21, 31, v20
	v_lshlrev_b64 v[40:41], 11, v[0:1]
	v_ashrrev_i32_e32 v25, 31, v24
	v_lshlrev_b64 v[16:17], 11, v[16:17]
	v_ashrrev_i32_e32 v27, 31, v26
	v_lshlrev_b64 v[18:19], 11, v[18:19]
	v_ashrrev_i32_e32 v29, 31, v28
	v_ashrrev_i32_e32 v31, 31, v30
	v_lshlrev_b32_e32 v12, 2, v2
	v_lshlrev_b64 v[20:21], 11, v[20:21]
	v_lshl_add_u64 v[40:41], v[22:23], 0, v[40:41]
	v_lshl_add_u64 v[24:25], v[24:25], 2, s[18:19]
	v_lshl_add_u64 v[86:87], v[22:23], 0, v[16:17]
	v_lshl_add_u64 v[26:27], v[26:27], 2, s[18:19]
	v_lshl_add_u64 v[88:89], v[22:23], 0, v[18:19]
	v_lshl_add_u64 v[28:29], v[28:29], 2, s[18:19]
	v_lshl_add_u64 v[30:31], v[30:31], 2, s[18:19]
	s_waitcnt vmcnt(0)
	s_barrier
	global_load_dwordx4 v[0:3], v12, s[24:25] offset:16
	global_load_dwordx4 v[4:7], v12, s[26:27] offset:16
	global_load_dwordx4 v[8:11], v12, s[24:25]
	s_nop 0
	global_load_dwordx4 v[12:15], v12, s[26:27]
	v_lshl_add_u64 v[90:91], v[22:23], 0, v[20:21]
	s_add_i32 s20, s47, s74
	s_cmpk_lt_i32 s20, 0x400
	s_cselect_b32 s20, s33, 0
	s_lshl_b32 s20, s20, 11
	v_lshl_add_u64 v[218:219], v[40:41], 0, s[20:21]
	v_lshl_add_u64 v[220:221], v[86:87], 0, s[20:21]
	v_lshl_add_u64 v[222:223], v[88:89], 0, s[20:21]
	v_lshl_add_u64 v[224:225], v[90:91], 0, s[20:21]
	global_load_dwordx2 v[92:93], v[24:25], off
	v_mov_b32_e32 v16, v226
	v_mov_b32_e32 v17, v227
	v_mov_b32_e32 v18, v228
	v_mov_b32_e32 v19, v229
	s_nop 0
	global_load_dwordx2 v[40:41], v[26:27], off
	v_mov_b32_e32 v20, v230
	v_mov_b32_e32 v21, v231
	v_mov_b32_e32 v22, v232
	v_mov_b32_e32 v23, v233
	s_nop 0
	global_load_dwordx2 v[86:87], v[28:29], off
	v_mov_b32_e32 v24, v234
	v_mov_b32_e32 v25, v235
	v_mov_b32_e32 v26, v236
	v_mov_b32_e32 v27, v237
	s_nop 0
	global_load_dwordx2 v[88:89], v[30:31], off
	s_nop 0
	v_mov_b32_e32 v28, v238
	v_mov_b32_e32 v29, v239
	v_mov_b32_e32 v30, v240
	v_mov_b32_e32 v31, v241
	v_add_lshl_u32 v32, v43, s14, 8
	v_lshl_add_u64 v[38:39], v[36:37], 0, v[32:33]
	global_load_dwordx4 v[132:135], v[38:39], off
	global_load_dwordx4 v[136:139], v[38:39], off offset:32
	global_load_dwordx4 v[140:143], v[38:39], off offset:64
	global_load_dwordx4 v[144:147], v[38:39], off offset:96
	global_load_dwordx4 v[148:151], v[38:39], off offset:128
	global_load_dwordx4 v[152:155], v[38:39], off offset:160
	global_load_dwordx4 v[156:159], v[38:39], off offset:192
	global_load_dwordx4 v[160:163], v[38:39], off offset:224
	v_add_lshl_u32 v212, s14, v45, 2
	global_load_dwordx4 v[110:113], v212, s[30:31]
	global_load_dwordx4 v[114:117], v212, s[30:31] offset:32
	global_load_dwordx4 v[118:121], v212, s[30:31] offset:64
	global_load_dwordx4 v[122:125], v212, s[30:31] offset:96
	v_or_b32_e32 v202, s14, v44
	v_lshlrev_b32_e32 v202, 1, v202
	v_mov_b32_e32 v203, 0
	v_lshl_add_u64 v[204:205], s[12:13], 0, v[202:203]
	v_add_u32_e32 v206, s48, v45
	v_ashrrev_i32_e32 v207, 31, v206
	v_lshlrev_b64 v[208:209], 11, v[206:207]
	v_lshl_add_u64 v[208:209], v[204:205], 0, v[208:209]
	global_load_ushort v170, v[208:209], off
	s_nop 0
	global_load_ushort v171, v[208:209], off offset:64
	v_add_u32_e32 v210, s48, v66
	v_ashrrev_i32_e32 v211, 31, v210
	v_lshlrev_b64 v[212:213], 11, v[210:211]
	v_lshl_add_u64 v[212:213], v[204:205], 0, v[212:213]
	global_load_ushort v172, v[212:213], off
	s_nop 0
	global_load_ushort v173, v[212:213], off offset:64
	v_add_u32_e32 v206, s48, v67
	v_ashrrev_i32_e32 v207, 31, v206
	v_lshlrev_b64 v[208:209], 11, v[206:207]
	v_lshl_add_u64 v[208:209], v[204:205], 0, v[208:209]
	global_load_ushort v174, v[208:209], off
	s_nop 0
	global_load_ushort v175, v[208:209], off offset:64
	v_add_u32_e32 v210, s48, v68
	v_ashrrev_i32_e32 v211, 31, v210
	v_lshlrev_b64 v[212:213], 11, v[210:211]
	v_lshl_add_u64 v[212:213], v[204:205], 0, v[212:213]
	global_load_ushort v176, v[212:213], off
	s_nop 0
	global_load_ushort v177, v[212:213], off offset:64
	v_add_u32_e32 v206, s48, v69
	v_ashrrev_i32_e32 v207, 31, v206
	v_lshlrev_b64 v[208:209], 11, v[206:207]
	v_lshl_add_u64 v[208:209], v[204:205], 0, v[208:209]
	global_load_ushort v178, v[208:209], off
	s_nop 0
	global_load_ushort v179, v[208:209], off offset:64
	v_add_u32_e32 v210, s48, v70
	v_ashrrev_i32_e32 v211, 31, v210
	v_lshlrev_b64 v[212:213], 11, v[210:211]
	v_lshl_add_u64 v[212:213], v[204:205], 0, v[212:213]
	global_load_ushort v180, v[212:213], off
	s_nop 0
	global_load_ushort v181, v[212:213], off offset:64
	v_add_u32_e32 v206, s48, v71
	v_ashrrev_i32_e32 v207, 31, v206
	v_lshlrev_b64 v[208:209], 11, v[206:207]
	v_lshl_add_u64 v[208:209], v[204:205], 0, v[208:209]
	global_load_ushort v182, v[208:209], off
	s_nop 0
	global_load_ushort v183, v[208:209], off offset:64
	v_add_u32_e32 v210, s48, v72
	v_ashrrev_i32_e32 v211, 31, v210
	v_lshlrev_b64 v[212:213], 11, v[210:211]
	v_lshl_add_u64 v[212:213], v[204:205], 0, v[212:213]
	global_load_ushort v184, v[212:213], off
	s_nop 0
	global_load_ushort v185, v[212:213], off offset:64
	v_add_u32_e32 v206, s48, v73
	v_ashrrev_i32_e32 v207, 31, v206
	v_lshlrev_b64 v[208:209], 11, v[206:207]
	v_lshl_add_u64 v[208:209], v[204:205], 0, v[208:209]
	global_load_ushort v186, v[208:209], off
	s_nop 0
; __device__ __forceinline__ void phase_mix0(const Params& p, LAS unsigned char* lds) {
;     ...
;         for (int q = 0; q < 4; ++q) { const int pc = tid + 512 * q, j = pc >> 4, d8 = (pc & 15) * 8;
;             const h16x8 v = *(const h16x8*)(V + (size_t)(t0 + j) * 1024 + g * 128 + d8);
;             const float mu = ST[2 * (t0 + j)] * (1.f / 1024.f), rs = rsqrtf(fmaxf(ST[2 * (t0 + j) + 1] * (1.f / 1024.f) - mu * mu, 0.f) + 1e-5f);
; #pragma unroll
;             for (int e = 0; e < 8; ++e) vnT[(d8 + e) * 136 + ((((j >> 3) ^ (pc & 15)) << 3) | (j & 7))] = (h16)(((float)v[e] - mu) * rs * lng[g * 128 + d8 + e] + lnb[g * 128 + d8 + e]); }
;     ...
;         for (int r = 0; r < 16; ++r) { const int i = itile * 32 + (r & 3) + 8 * (r >> 2) + 4 * (lane >> 5); const size_t t = (size_t)(t0 + i);
;             const float bias = bs[g * 128 + i];
;             const int d0 = g * 128 + dt0 * 32 + (lane & 31);
;             YC[t * 2048 + 1024 + d0] = (h16)((acc0[r] + bias) * (float)U[t * 1024 + d0]);
;             YC[t * 2048 + 1024 + d0 + 32] = (h16)((acc1[r] + bias) * (float)U[t * 1024 + d0 + 32]); }
	global_load_ushort v187, v[208:209], off offset:64
	v_add_u32_e32 v210, s48, v74
	v_ashrrev_i32_e32 v211, 31, v210
	v_lshlrev_b64 v[212:213], 11, v[210:211]
	v_lshl_add_u64 v[212:213], v[204:205], 0, v[212:213]
	global_load_ushort v188, v[212:213], off
	s_nop 0
	global_load_ushort v189, v[212:213], off offset:64
	v_add_u32_e32 v206, s48, v75
	v_ashrrev_i32_e32 v207, 31, v206
	v_lshlrev_b64 v[208:209], 11, v[206:207]
	v_lshl_add_u64 v[208:209], v[204:205], 0, v[208:209]
	global_load_ushort v190, v[208:209], off
	s_nop 0
	global_load_ushort v191, v[208:209], off offset:64
	v_add_u32_e32 v210, s48, v76
	v_ashrrev_i32_e32 v211, 31, v210
	v_lshlrev_b64 v[212:213], 11, v[210:211]
	v_lshl_add_u64 v[212:213], v[204:205], 0, v[212:213]
	global_load_ushort v192, v[212:213], off
	s_nop 0
	global_load_ushort v193, v[212:213], off offset:64
	v_add_u32_e32 v206, s48, v77
	v_ashrrev_i32_e32 v207, 31, v206
	v_lshlrev_b64 v[208:209], 11, v[206:207]
	v_lshl_add_u64 v[208:209], v[204:205], 0, v[208:209]
	global_load_ushort v194, v[208:209], off
	s_nop 0
	global_load_ushort v195, v[208:209], off offset:64
	v_add_u32_e32 v210, s48, v78
	v_ashrrev_i32_e32 v211, 31, v210
	v_lshlrev_b64 v[212:213], 11, v[210:211]
	v_lshl_add_u64 v[212:213], v[204:205], 0, v[212:213]
	global_load_ushort v196, v[212:213], off
	s_nop 0
	global_load_ushort v197, v[212:213], off offset:64
	v_add_u32_e32 v206, s48, v79
	v_ashrrev_i32_e32 v207, 31, v206
	v_lshlrev_b64 v[208:209], 11, v[206:207]
	v_lshl_add_u64 v[208:209], v[204:205], 0, v[208:209]
	global_load_ushort v198, v[208:209], off
	s_nop 0
	global_load_ushort v199, v[208:209], off offset:64
	v_add_u32_e32 v210, s48, v80
	v_ashrrev_i32_e32 v211, 31, v210
	v_lshlrev_b64 v[212:213], 11, v[210:211]
	v_lshl_add_u64 v[212:213], v[204:205], 0, v[212:213]
	global_load_ushort v200, v[212:213], off
	s_nop 0
	global_load_ushort v201, v[212:213], off offset:64
	s_add_i32 s47, s47, s74
	s_add_i32 s29, s29, s33
	s_waitcnt vmcnt(47)
	v_pk_mul_f32 v[90:91], v[92:93], s[22:23] op_sel_hi:[1,0]
	s_waitcnt vmcnt(47)
	v_cvt_f32_f16_e32 v32, v16
	v_cvt_f32_f16_sdwa v85, v16 dst_sel:DWORD dst_unused:UNUSED_PAD src0_sel:WORD_1
	v_cvt_f32_f16_e32 v92, v17
	v_cvt_f32_f16_sdwa v93, v17 dst_sel:DWORD dst_unused:UNUSED_PAD src0_sel:WORD_1
	v_cvt_f32_f16_e32 v94, v18
	v_cvt_f32_f16_sdwa v95, v18 dst_sel:DWORD dst_unused:UNUSED_PAD src0_sel:WORD_1
	v_cvt_f32_f16_e32 v96, v19
	v_cvt_f32_f16_sdwa v97, v19 dst_sel:DWORD dst_unused:UNUSED_PAD src0_sel:WORD_1
	s_waitcnt vmcnt(46)
	v_pk_mul_f32 v[16:17], v[40:41], s[22:23] op_sel_hi:[1,0]
	s_waitcnt vmcnt(46)
	v_cvt_f32_f16_e32 v40, v20
	v_cvt_f32_f16_sdwa v41, v20 dst_sel:DWORD dst_unused:UNUSED_PAD src0_sel:WORD_1
	v_cvt_f32_f16_e32 v98, v21
	v_cvt_f32_f16_sdwa v99, v21 dst_sel:DWORD dst_unused:UNUSED_PAD src0_sel:WORD_1
	v_cvt_f32_f16_e32 v100, v22
	v_cvt_f32_f16_sdwa v22, v22 dst_sel:DWORD dst_unused:UNUSED_PAD src0_sel:WORD_1
	v_cvt_f32_f16_e32 v101, v23
	v_cvt_f32_f16_sdwa v23, v23 dst_sel:DWORD dst_unused:UNUSED_PAD src0_sel:WORD_1
	s_waitcnt vmcnt(45)
	v_pk_mul_f32 v[18:19], v[86:87], s[22:23] op_sel_hi:[1,0]
	s_waitcnt vmcnt(45)
	v_cvt_f32_f16_e32 v86, v24
	v_cvt_f32_f16_sdwa v24, v24 dst_sel:DWORD dst_unused:UNUSED_PAD src0_sel:WORD_1
	v_cvt_f32_f16_e32 v87, v25
	v_cvt_f32_f16_sdwa v25, v25 dst_sel:DWORD dst_unused:UNUSED_PAD src0_sel:WORD_1
	v_cvt_f32_f16_e32 v102, v26
	v_cvt_f32_f16_sdwa v26, v26 dst_sel:DWORD dst_unused:UNUSED_PAD src0_sel:WORD_1
	v_cvt_f32_f16_e32 v103, v27
	v_cvt_f32_f16_sdwa v27, v27 dst_sel:DWORD dst_unused:UNUSED_PAD src0_sel:WORD_1
	s_waitcnt vmcnt(44)
	v_pk_mul_f32 v[20:21], v[88:89], s[22:23] op_sel_hi:[1,0]
	s_waitcnt vmcnt(44)
	v_cvt_f32_f16_e32 v88, v28
	v_cvt_f32_f16_sdwa v28, v28 dst_sel:DWORD dst_unused:UNUSED_PAD src0_sel:WORD_1
	v_cvt_f32_f16_e32 v89, v29
	v_cvt_f32_f16_sdwa v29, v29 dst_sel:DWORD dst_unused:UNUSED_PAD src0_sel:WORD_1
	v_cvt_f32_f16_e32 v104, v30
	v_cvt_f32_f16_sdwa v30, v30 dst_sel:DWORD dst_unused:UNUSED_PAD src0_sel:WORD_1
	v_cvt_f32_f16_e32 v105, v31
	v_cvt_f32_f16_sdwa v31, v31 dst_sel:DWORD dst_unused:UNUSED_PAD src0_sel:WORD_1
	v_fma_f32 v91, -v90, v90, v91
	v_fma_f32 v17, -v16, v16, v17
	v_fma_f32 v19, -v18, v18, v19
	v_fma_f32 v21, -v20, v20, v21
	v_max_f32_e32 v91, 0, v91
	v_max_f32_e32 v17, 0, v17
	v_max_f32_e32 v19, 0, v19
	v_max_f32_e32 v21, 0, v21
	v_add_f32_e32 v91, 0x3727c5ac, v91
	v_add_f32_e32 v17, 0x3727c5ac, v17
	v_add_f32_e32 v19, 0x3727c5ac, v19
	v_add_f32_e32 v21, 0x3727c5ac, v21
	v_mul_f32_e32 v106, 0x4b800000, v91
	v_sub_f32_e32 v32, v32, v90
	v_sub_f32_e32 v85, v85, v90
	v_sub_f32_e32 v92, v92, v90
	v_sub_f32_e32 v93, v93, v90
	v_sub_f32_e32 v94, v94, v90
	v_sub_f32_e32 v95, v95, v90
	v_sub_f32_e32 v96, v96, v90
	v_sub_f32_e32 v90, v97, v90
	v_mul_f32_e32 v97, 0x4b800000, v17
	v_cmp_gt_f32_e32 vcc, s46, v17
	v_sub_f32_e32 v40, v40, v16
	v_sub_f32_e32 v41, v41, v16
	v_sub_f32_e32 v98, v98, v16
	v_sub_f32_e32 v99, v99, v16
	v_sub_f32_e32 v100, v100, v16
	v_sub_f32_e32 v22, v22, v16
	v_sub_f32_e32 v101, v101, v16
	v_sub_f32_e32 v16, v23, v16
	v_mul_f32_e32 v23, 0x4b800000, v19
	v_cmp_gt_f32_e64 s[0:1], s46, v19
	v_cmp_gt_f32_e64 s[6:7], s46, v91
	v_sub_f32_e32 v86, v86, v18
	v_sub_f32_e32 v24, v24, v18
	v_sub_f32_e32 v87, v87, v18
	v_sub_f32_e32 v25, v25, v18
	v_sub_f32_e32 v102, v102, v18
	v_sub_f32_e32 v26, v26, v18
	v_sub_f32_e32 v103, v103, v18
	v_sub_f32_e32 v18, v27, v18
	v_mul_f32_e32 v27, 0x4b800000, v21
	v_cmp_gt_f32_e64 s[4:5], s46, v21
	v_sub_f32_e32 v88, v88, v20
	v_sub_f32_e32 v28, v28, v20
	v_sub_f32_e32 v89, v89, v20
	v_sub_f32_e32 v29, v29, v20
	v_sub_f32_e32 v104, v104, v20
	v_sub_f32_e32 v30, v30, v20
; #define LAS __attribute__((address_space(3)))
; __device__ __forceinline__ void phase_mix0(const Params& p, LAS unsigned char* lds) {
;     ...
;             const float mu = ST[2 * (t0 + j)] * (1.f / 1024.f), rs = rsqrtf(fmaxf(ST[2 * (t0 + j) + 1] * (1.f / 1024.f) - mu * mu, 0.f) + 1e-5f);
; #pragma unroll
;             for (int e = 0; e < 8; ++e) vnT[(d8 + e) * 136 + ((((j >> 3) ^ (pc & 15)) << 3) | (j & 7))] = (h16)(((float)v[e] - mu) * rs * lng[g * 128 + d8 + e] + lnb[g * 128 + d8 + e]); }
;     ...
; #pragma unroll
;         for (int ks = 0; ks < 8; ++ks) {
;             const h16x8 a = *(const h16x8*)(Arow + 16 * ks);
;             const int jg = 2 * ks + (lane >> 5);
;             const h16x8 b0 = *(const LAS h16x8*)(B0p + ((jg ^ ((d0_ >> 3) & 15)) << 3)), b1 = *(const LAS h16x8*)(B1p + ((jg ^ ((d1_ >> 3) & 15)) << 3));
;             acc0 = __builtin_amdgcn_mfma_f32_32x32x16_f16(a, b0, acc0, 0, 0, 0);
;             acc1 = __builtin_amdgcn_mfma_f32_32x32x16_f16(a, b1, acc1, 0, 0, 0);
;         }
	v_sub_f32_e32 v105, v105, v20
	v_sub_f32_e32 v20, v31, v20
	v_cndmask_b32_e64 v31, v91, v106, s[6:7]
	v_cndmask_b32_e32 v17, v17, v97, vcc
	v_cndmask_b32_e64 v19, v19, v23, s[0:1]
	v_cndmask_b32_e64 v21, v21, v27, s[4:5]
	v_rsq_f32_e32 v23, v31
	v_rsq_f32_e32 v17, v17
	v_rsq_f32_e32 v19, v19
	v_rsq_f32_e32 v21, v21
	v_mul_f32_e32 v27, 0x45800000, v23
	v_mul_f32_e32 v31, 0x45800000, v17
	v_mul_f32_e32 v91, 0x45800000, v19
	v_mul_f32_e32 v97, 0x45800000, v21
	v_cndmask_b32_e64 v23, v23, v27, s[6:7]
	v_cndmask_b32_e32 v17, v17, v31, vcc
	v_cndmask_b32_e64 v19, v19, v91, s[0:1]
	v_cndmask_b32_e64 v21, v21, v97, s[4:5]
	v_mul_f32_e32 v27, v32, v23
	v_mul_f32_e32 v31, v85, v23
	v_mul_f32_e32 v32, v92, v23
	v_mul_f32_e32 v85, v93, v23
	v_mul_f32_e32 v91, v94, v23
	v_mul_f32_e32 v92, v95, v23
	v_mul_f32_e32 v93, v96, v23
	v_mul_f32_e32 v23, v90, v23
	v_mul_f32_e32 v40, v40, v17
	v_mul_f32_e32 v41, v41, v17
	v_mul_f32_e32 v90, v98, v17
	v_mul_f32_e32 v94, v99, v17
	v_mul_f32_e32 v95, v100, v17
	v_mul_f32_e32 v22, v22, v17
	v_mul_f32_e32 v96, v101, v17
	v_mul_f32_e32 v16, v16, v17
	v_mul_f32_e32 v17, v86, v19
	v_mul_f32_e32 v86, v87, v19
	v_mul_f32_e32 v87, v102, v19
	v_mul_f32_e32 v18, v18, v19
	v_mul_f32_e32 v24, v24, v19
	v_mul_f32_e32 v25, v25, v19
	v_mul_f32_e32 v26, v26, v19
	v_mul_f32_e32 v97, v103, v19
	v_mul_f32_e32 v19, v88, v21
	v_mul_f32_e32 v28, v28, v21
	v_mul_f32_e32 v88, v89, v21
	v_mul_f32_e32 v29, v29, v21
	v_mul_f32_e32 v89, v104, v21
	v_mul_f32_e32 v30, v30, v21
	v_mul_f32_e32 v98, v105, v21
	v_mul_f32_e32 v20, v20, v21
	v_fma_mixlo_f16 v21, v8, v27, v12
	v_fma_mixlo_f16 v16, v3, v16, v7
	v_fma_mixlo_f16 v17, v8, v17, v12
	v_fma_mixlo_f16 v86, v10, v86, v14
	v_fma_mixlo_f16 v87, v0, v87, v4
	v_fma_mixlo_f16 v18, v3, v18, v7
	v_fma_mixlo_f16 v27, v9, v31, v13
	v_fma_mixlo_f16 v31, v10, v32, v14
	v_fma_mixlo_f16 v32, v85, v11, v15
	v_fma_mixlo_f16 v85, v91, v0, v4
	v_fma_mixlo_f16 v91, v92, v1, v5
	v_fma_mixlo_f16 v92, v93, v2, v6
	v_fma_mixlo_f16 v23, v23, v3, v7
	v_fma_mixlo_f16 v40, v8, v40, v12
	v_fma_mixlo_f16 v41, v9, v41, v13
	v_fma_mixlo_f16 v90, v10, v90, v14
	v_fma_mixlo_f16 v93, v11, v94, v15
	v_fma_mixlo_f16 v94, v0, v95, v4
	v_fma_mixlo_f16 v22, v1, v22, v5
	v_fma_mixlo_f16 v95, v2, v96, v6
	v_fma_mixlo_f16 v24, v9, v24, v13
	v_fma_mixlo_f16 v25, v11, v25, v15
	v_fma_mixlo_f16 v26, v1, v26, v5
	v_fma_mixlo_f16 v96, v2, v97, v6
	v_fma_mixlo_f16 v8, v8, v19, v12
	v_fma_mixlo_f16 v9, v9, v28, v13
	v_fma_mixlo_f16 v10, v10, v88, v14
	v_fma_mixlo_f16 v11, v11, v29, v15
	v_fma_mixlo_f16 v0, v0, v89, v4
	v_fma_mixlo_f16 v1, v1, v30, v5
	v_fma_mixlo_f16 v2, v2, v98, v6
	v_fma_mixlo_f16 v3, v3, v20, v7
	ds_write_b16 v81, v21
	ds_write_b16 v81, v27 offset:272
	ds_write_b16 v81, v31 offset:544
	ds_write_b16 v81, v32 offset:816
	ds_write_b16 v81, v85 offset:1088
	ds_write_b16 v81, v91 offset:1360
	ds_write_b16 v81, v92 offset:1632
	ds_write_b16 v81, v23 offset:1904
	ds_write_b16 v82, v40
	ds_write_b16 v82, v41 offset:272
	ds_write_b16 v82, v90 offset:544
	ds_write_b16 v82, v93 offset:816
	ds_write_b16 v82, v94 offset:1088
	ds_write_b16 v82, v22 offset:1360
	ds_write_b16 v82, v95 offset:1632
	ds_write_b16 v82, v16 offset:1904
	ds_write_b16 v83, v17
	ds_write_b16 v83, v24 offset:272
	ds_write_b16 v83, v86 offset:544
	ds_write_b16 v83, v25 offset:816
	ds_write_b16 v83, v87 offset:1088
	ds_write_b16 v83, v26 offset:1360
	ds_write_b16 v83, v96 offset:1632
	ds_write_b16 v83, v18 offset:1904
	ds_write_b16 v84, v8
	ds_write_b16 v84, v9 offset:272
	ds_write_b16 v84, v10 offset:544
	ds_write_b16 v84, v11 offset:816
	ds_write_b16 v84, v0 offset:1088
	ds_write_b16 v84, v1 offset:1360
	ds_write_b16 v84, v2 offset:1632
	ds_write_b16 v84, v3 offset:1904
	s_waitcnt lgkmcnt(0)
	s_barrier
	global_load_dwordx4 v[226:229], v[218:219], off
	global_load_dwordx4 v[230:233], v[220:221], off
	global_load_dwordx4 v[234:237], v[222:223], off
	global_load_dwordx4 v[238:241], v[224:225], off
	ds_read_b128 v[0:3], v50
	ds_read_b128 v[20:23], v51
	ds_read_b128 v[90:93], v52
	ds_read_b128 v[94:97], v53
	s_waitcnt vmcnt(40) lgkmcnt(3)
	v_mfma_f32_32x32x16_f16 v[0:15], v[132:135], v[0:3], 0
	s_waitcnt lgkmcnt(2)
	v_mfma_f32_32x32x16_f16 v[16:31], v[132:135], v[20:23], 0
	ds_read_b128 v[98:101], v54
	ds_read_b128 v[102:105], v55
	s_waitcnt lgkmcnt(3)
	v_mfma_f32_32x32x16_f16 v[0:15], v[136:139], v[90:93], v[0:15]
	s_waitcnt lgkmcnt(2)
	v_mfma_f32_32x32x16_f16 v[16:31], v[136:139], v[94:97], v[16:31]
	ds_read_b128 v[90:93], v56
	ds_read_b128 v[94:97], v57
	s_waitcnt lgkmcnt(3)
	v_mfma_f32_32x32x16_f16 v[0:15], v[140:143], v[98:101], v[0:15]
	s_waitcnt lgkmcnt(2)
	v_mfma_f32_32x32x16_f16 v[16:31], v[140:143], v[102:105], v[16:31]
	ds_read_b128 v[98:101], v58
	ds_read_b128 v[102:105], v59
	s_waitcnt lgkmcnt(3)
	v_mfma_f32_32x32x16_f16 v[0:15], v[144:147], v[90:93], v[0:15]
	s_waitcnt lgkmcnt(2)
	v_mfma_f32_32x32x16_f16 v[16:31], v[144:147], v[94:97], v[16:31]
	ds_read_b128 v[90:93], v60
	ds_read_b128 v[94:97], v61
	s_waitcnt lgkmcnt(3)
	v_mfma_f32_32x32x16_f16 v[0:15], v[148:151], v[98:101], v[0:15]
	s_waitcnt lgkmcnt(2)
	v_mfma_f32_32x32x16_f16 v[16:31], v[148:151], v[102:105], v[16:31]
	ds_read_b128 v[98:101], v62
	ds_read_b128 v[102:105], v63
	s_waitcnt lgkmcnt(3)
	v_mfma_f32_32x32x16_f16 v[0:15], v[152:155], v[90:93], v[0:15]
	s_waitcnt lgkmcnt(2)
	v_mfma_f32_32x32x16_f16 v[16:31], v[152:155], v[94:97], v[16:31]
	ds_read_b128 v[90:93], v64
	ds_read_b128 v[94:97], v65
	s_waitcnt lgkmcnt(3)
	v_mfma_f32_32x32x16_f16 v[0:15], v[156:159], v[98:101], v[0:15]
	s_waitcnt lgkmcnt(2)
	v_mfma_f32_32x32x16_f16 v[16:31], v[156:159], v[102:105], v[16:31]
	s_waitcnt lgkmcnt(1)
; __device__ __forceinline__ void phase_mix0(const Params& p, LAS unsigned char* lds) {
;     ...
;             acc0 = __builtin_amdgcn_mfma_f32_32x32x16_f16(a, b0, acc0, 0, 0, 0);
;             acc1 = __builtin_amdgcn_mfma_f32_32x32x16_f16(a, b1, acc1, 0, 0, 0);
;         }
; #pragma unroll
;         for (int r = 0; r < 16; ++r) { const int i = itile * 32 + (r & 3) + 8 * (r >> 2) + 4 * (lane >> 5); const size_t t = (size_t)(t0 + i);
;             const float bias = bs[g * 128 + i];
;             const int d0 = g * 128 + dt0 * 32 + (lane & 31);
;             YC[t * 2048 + 1024 + d0] = (h16)((acc0[r] + bias) * (float)U[t * 1024 + d0]);
;             YC[t * 2048 + 1024 + d0 + 32] = (h16)((acc1[r] + bias) * (float)U[t * 1024 + d0 + 32]); }
	v_mfma_f32_32x32x16_f16 v[0:15], v[160:163], v[90:93], v[0:15]
	s_waitcnt lgkmcnt(0)
	v_mfma_f32_32x32x16_f16 v[16:31], v[160:163], v[94:97], v[16:31]
	s_add_i32 s23, s23, s28
	v_or_b32_e32 v202, s14, v44
	v_lshlrev_b32_e32 v202, 1, v202
	v_mov_b32_e32 v203, 0
	v_lshl_add_u64 v[204:205], s[10:11], 0, v[202:203]
	s_waitcnt vmcnt(4)
	s_nop 7
	s_nop 7
	s_nop 7
	v_add_f32_e32 v214, v0, v110
	v_add_f32_e32 v215, v16, v110
	v_add_u32_e32 v206, s48, v45
	v_ashrrev_i32_e32 v207, 31, v206
	v_fma_mixlo_f16 v214, v214, v170, 0 op_sel_hi:[0,1,0]
	v_fma_mixlo_f16 v215, v215, v171, 0 op_sel_hi:[0,1,0]
	v_lshlrev_b64 v[208:209], 12, v[206:207]
	v_lshl_add_u64 v[208:209], v[204:205], 0, v[208:209]
	global_store_short v[208:209], v214, off offset:2048
	global_store_short v[208:209], v215, off offset:2112
	v_add_f32_e32 v216, v1, v111
	v_add_f32_e32 v217, v17, v111
	v_add_u32_e32 v210, s48, v66
	v_ashrrev_i32_e32 v211, 31, v210
	v_fma_mixlo_f16 v216, v216, v172, 0 op_sel_hi:[0,1,0]
	v_fma_mixlo_f16 v217, v217, v173, 0 op_sel_hi:[0,1,0]
	v_lshlrev_b64 v[212:213], 12, v[210:211]
	v_lshl_add_u64 v[212:213], v[204:205], 0, v[212:213]
	global_store_short v[212:213], v216, off offset:2048
	global_store_short v[212:213], v217, off offset:2112
	v_add_f32_e32 v214, v2, v112
	v_add_f32_e32 v215, v18, v112
	v_add_u32_e32 v206, s48, v67
	v_ashrrev_i32_e32 v207, 31, v206
	v_fma_mixlo_f16 v214, v214, v174, 0 op_sel_hi:[0,1,0]
	v_fma_mixlo_f16 v215, v215, v175, 0 op_sel_hi:[0,1,0]
	v_lshlrev_b64 v[208:209], 12, v[206:207]
	v_lshl_add_u64 v[208:209], v[204:205], 0, v[208:209]
	global_store_short v[208:209], v214, off offset:2048
	global_store_short v[208:209], v215, off offset:2112
	v_add_f32_e32 v216, v3, v113
	v_add_f32_e32 v217, v19, v113
	v_add_u32_e32 v210, s48, v68
	v_ashrrev_i32_e32 v211, 31, v210
	v_fma_mixlo_f16 v216, v216, v176, 0 op_sel_hi:[0,1,0]
	v_fma_mixlo_f16 v217, v217, v177, 0 op_sel_hi:[0,1,0]
	v_lshlrev_b64 v[212:213], 12, v[210:211]
	v_lshl_add_u64 v[212:213], v[204:205], 0, v[212:213]
	global_store_short v[212:213], v216, off offset:2048
	global_store_short v[212:213], v217, off offset:2112
	v_add_f32_e32 v214, v4, v114
	v_add_f32_e32 v215, v20, v114
	v_add_u32_e32 v206, s48, v69
	v_ashrrev_i32_e32 v207, 31, v206
	v_fma_mixlo_f16 v214, v214, v178, 0 op_sel_hi:[0,1,0]
	v_fma_mixlo_f16 v215, v215, v179, 0 op_sel_hi:[0,1,0]
	v_lshlrev_b64 v[208:209], 12, v[206:207]
	v_lshl_add_u64 v[208:209], v[204:205], 0, v[208:209]
	global_store_short v[208:209], v214, off offset:2048
	global_store_short v[208:209], v215, off offset:2112
	v_add_f32_e32 v216, v5, v115
	v_add_f32_e32 v217, v21, v115
	v_add_u32_e32 v210, s48, v70
	v_ashrrev_i32_e32 v211, 31, v210
	v_fma_mixlo_f16 v216, v216, v180, 0 op_sel_hi:[0,1,0]
	v_fma_mixlo_f16 v217, v217, v181, 0 op_sel_hi:[0,1,0]
	v_lshlrev_b64 v[212:213], 12, v[210:211]
	v_lshl_add_u64 v[212:213], v[204:205], 0, v[212:213]
	global_store_short v[212:213], v216, off offset:2048
	global_store_short v[212:213], v217, off offset:2112
	v_add_f32_e32 v214, v6, v116
	v_add_f32_e32 v215, v22, v116
	v_add_u32_e32 v206, s48, v71
	v_ashrrev_i32_e32 v207, 31, v206
	v_fma_mixlo_f16 v214, v214, v182, 0 op_sel_hi:[0,1,0]
	v_fma_mixlo_f16 v215, v215, v183, 0 op_sel_hi:[0,1,0]
	v_lshlrev_b64 v[208:209], 12, v[206:207]
	v_lshl_add_u64 v[208:209], v[204:205], 0, v[208:209]
	global_store_short v[208:209], v214, off offset:2048
	global_store_short v[208:209], v215, off offset:2112
	v_add_f32_e32 v216, v7, v117
	v_add_f32_e32 v217, v23, v117
	v_add_u32_e32 v210, s48, v72
	v_ashrrev_i32_e32 v211, 31, v210
	v_fma_mixlo_f16 v216, v216, v184, 0 op_sel_hi:[0,1,0]
	v_fma_mixlo_f16 v217, v217, v185, 0 op_sel_hi:[0,1,0]
	v_lshlrev_b64 v[212:213], 12, v[210:211]
; __device__ __forceinline__ void phase_mix0(const Params& p, LAS unsigned char* lds) {
;     ...
;         for (int r = 0; r < 16; ++r) { const int i = itile * 32 + (r & 3) + 8 * (r >> 2) + 4 * (lane >> 5); const size_t t = (size_t)(t0 + i);
;             const float bias = bs[g * 128 + i];
;             const int d0 = g * 128 + dt0 * 32 + (lane & 31);
;             YC[t * 2048 + 1024 + d0] = (h16)((acc0[r] + bias) * (float)U[t * 1024 + d0]);
;             YC[t * 2048 + 1024 + d0 + 32] = (h16)((acc1[r] + bias) * (float)U[t * 1024 + d0 + 32]); }
	v_lshl_add_u64 v[212:213], v[204:205], 0, v[212:213]
	global_store_short v[212:213], v216, off offset:2048
	global_store_short v[212:213], v217, off offset:2112
	v_add_f32_e32 v214, v8, v118
	v_add_f32_e32 v215, v24, v118
	v_add_u32_e32 v206, s48, v73
	v_ashrrev_i32_e32 v207, 31, v206
	v_fma_mixlo_f16 v214, v214, v186, 0 op_sel_hi:[0,1,0]
	v_fma_mixlo_f16 v215, v215, v187, 0 op_sel_hi:[0,1,0]
	v_lshlrev_b64 v[208:209], 12, v[206:207]
	v_lshl_add_u64 v[208:209], v[204:205], 0, v[208:209]
	global_store_short v[208:209], v214, off offset:2048
	global_store_short v[208:209], v215, off offset:2112
	v_add_f32_e32 v216, v9, v119
	v_add_f32_e32 v217, v25, v119
	v_add_u32_e32 v210, s48, v74
	v_ashrrev_i32_e32 v211, 31, v210
	v_fma_mixlo_f16 v216, v216, v188, 0 op_sel_hi:[0,1,0]
	v_fma_mixlo_f16 v217, v217, v189, 0 op_sel_hi:[0,1,0]
	v_lshlrev_b64 v[212:213], 12, v[210:211]
	v_lshl_add_u64 v[212:213], v[204:205], 0, v[212:213]
	global_store_short v[212:213], v216, off offset:2048
	global_store_short v[212:213], v217, off offset:2112
	v_add_f32_e32 v214, v10, v120
	v_add_f32_e32 v215, v26, v120
	v_add_u32_e32 v206, s48, v75
	v_ashrrev_i32_e32 v207, 31, v206
	v_fma_mixlo_f16 v214, v214, v190, 0 op_sel_hi:[0,1,0]
	v_fma_mixlo_f16 v215, v215, v191, 0 op_sel_hi:[0,1,0]
	v_lshlrev_b64 v[208:209], 12, v[206:207]
	v_lshl_add_u64 v[208:209], v[204:205], 0, v[208:209]
	global_store_short v[208:209], v214, off offset:2048
	global_store_short v[208:209], v215, off offset:2112
	v_add_f32_e32 v216, v11, v121
	v_add_f32_e32 v217, v27, v121
	v_add_u32_e32 v210, s48, v76
	v_ashrrev_i32_e32 v211, 31, v210
	v_fma_mixlo_f16 v216, v216, v192, 0 op_sel_hi:[0,1,0]
	v_fma_mixlo_f16 v217, v217, v193, 0 op_sel_hi:[0,1,0]
	v_lshlrev_b64 v[212:213], 12, v[210:211]
	v_lshl_add_u64 v[212:213], v[204:205], 0, v[212:213]
	global_store_short v[212:213], v216, off offset:2048
	global_store_short v[212:213], v217, off offset:2112
	v_add_f32_e32 v214, v12, v122
	v_add_f32_e32 v215, v28, v122
	v_add_u32_e32 v206, s48, v77
	v_ashrrev_i32_e32 v207, 31, v206
	v_fma_mixlo_f16 v214, v214, v194, 0 op_sel_hi:[0,1,0]
	v_fma_mixlo_f16 v215, v215, v195, 0 op_sel_hi:[0,1,0]
	v_lshlrev_b64 v[208:209], 12, v[206:207]
	v_lshl_add_u64 v[208:209], v[204:205], 0, v[208:209]
	global_store_short v[208:209], v214, off offset:2048
	global_store_short v[208:209], v215, off offset:2112
	v_add_f32_e32 v216, v13, v123
	v_add_f32_e32 v217, v29, v123
	v_add_u32_e32 v210, s48, v78
	v_ashrrev_i32_e32 v211, 31, v210
	v_fma_mixlo_f16 v216, v216, v196, 0 op_sel_hi:[0,1,0]
	v_fma_mixlo_f16 v217, v217, v197, 0 op_sel_hi:[0,1,0]
	v_lshlrev_b64 v[212:213], 12, v[210:211]
	v_lshl_add_u64 v[212:213], v[204:205], 0, v[212:213]
	global_store_short v[212:213], v216, off offset:2048
	global_store_short v[212:213], v217, off offset:2112
	v_add_f32_e32 v214, v14, v124
	v_add_f32_e32 v215, v30, v124
	v_add_u32_e32 v206, s48, v79
	v_ashrrev_i32_e32 v207, 31, v206
	v_fma_mixlo_f16 v214, v214, v198, 0 op_sel_hi:[0,1,0]
	v_fma_mixlo_f16 v215, v215, v199, 0 op_sel_hi:[0,1,0]
	v_lshlrev_b64 v[208:209], 12, v[206:207]
	v_lshl_add_u64 v[208:209], v[204:205], 0, v[208:209]
	global_store_short v[208:209], v214, off offset:2048
	global_store_short v[208:209], v215, off offset:2112
	v_add_f32_e32 v216, v15, v125
	v_add_f32_e32 v217, v31, v125
	v_add_u32_e32 v210, s48, v80
	v_ashrrev_i32_e32 v211, 31, v210
	v_fma_mixlo_f16 v216, v216, v200, 0 op_sel_hi:[0,1,0]
	v_fma_mixlo_f16 v217, v217, v201, 0 op_sel_hi:[0,1,0]
	v_lshlrev_b64 v[212:213], 12, v[210:211]
	v_lshl_add_u64 v[212:213], v[204:205], 0, v[212:213]
	global_store_short v[212:213], v216, off offset:2048
	global_store_short v[212:213], v217, off offset:2112
	s_cmpk_lt_i32 s47, 0x400
	s_cbranch_scc1 .LBB0_289
